# c13 with every GEMM inner-loop head placed at byte offset 28 mod 64 (.p2align 6 + 7 s_nop before the loop label); code-placement sweep, no instruction change inside the loops
# speedup vs baseline: 1.0084x; 1.0084x over previous
.LBB0_165:
	s_ashr_i32 s29, s28, 31
	s_lshl_b64 s[30:31], s[28:29], 19
	s_add_u32 s30, s27, s30
	s_addc_u32 s31, s44, s31
	s_and_b64 s[34:35], s[4:5], exec
	s_cselect_b32 s7, s31, s39
	s_cselect_b32 s29, s30, s38
	s_ashr_i32 s19, s18, 31
	s_lshl_b64 s[34:35], s[18:19], 19
	s_add_u32 s34, s45, s34
	s_addc_u32 s35, s46, s35
	s_and_b64 s[42:43], s[4:5], exec
	s_cselect_b32 s19, s35, s41
	s_cselect_b32 s61, s34, s40
	s_add_u32 s38, s38, 0x40080
	s_addc_u32 s39, s39, 0
	s_add_u32 s63, s40, 0x100
	v_mov_b32_e32 v0, 0
	s_addc_u32 s65, s41, 0
	s_mov_b32 s66, -2
	v_mov_b32_e32 v1, v0
	v_mov_b32_e32 v2, v0
	v_mov_b32_e32 v3, v0
	v_mov_b32_e32 v4, v0
	v_mov_b32_e32 v5, v0
	v_mov_b32_e32 v6, v0
	v_mov_b32_e32 v7, v0
	v_mov_b32_e32 v16, v0
	v_mov_b32_e32 v17, v0
	v_mov_b32_e32 v18, v0
	v_mov_b32_e32 v19, v0
	v_mov_b32_e32 v20, v0
	v_mov_b32_e32 v21, v0
	v_mov_b32_e32 v22, v0
	v_mov_b32_e32 v23, v0
	v_mov_b32_e32 v32, v0
	v_mov_b32_e32 v33, v0
	v_mov_b32_e32 v34, v0
	v_mov_b32_e32 v35, v0
	v_mov_b32_e32 v36, v0
	v_mov_b32_e32 v37, v0
	v_mov_b32_e32 v38, v0
	v_mov_b32_e32 v39, v0
	v_mov_b32_e32 v48, v0
	v_mov_b32_e32 v49, v0
	v_mov_b32_e32 v50, v0
	v_mov_b32_e32 v51, v0
	v_mov_b32_e32 v52, v0
	v_mov_b32_e32 v53, v0
	v_mov_b32_e32 v54, v0
	v_mov_b32_e32 v55, v0
	v_mov_b32_e32 v8, v0
	v_mov_b32_e32 v9, v0
	v_mov_b32_e32 v10, v0
	v_mov_b32_e32 v11, v0
	v_mov_b32_e32 v12, v0
	v_mov_b32_e32 v13, v0
	v_mov_b32_e32 v14, v0
	v_mov_b32_e32 v15, v0
	v_mov_b32_e32 v24, v0
	v_mov_b32_e32 v25, v0
	v_mov_b32_e32 v26, v0
	v_mov_b32_e32 v27, v0
	v_mov_b32_e32 v28, v0
	v_mov_b32_e32 v29, v0
	v_mov_b32_e32 v30, v0
	v_mov_b32_e32 v31, v0
	v_mov_b32_e32 v40, v0
	v_mov_b32_e32 v41, v0
	v_mov_b32_e32 v42, v0
	v_mov_b32_e32 v43, v0
	v_mov_b32_e32 v44, v0
	v_mov_b32_e32 v45, v0
	v_mov_b32_e32 v46, v0
	v_mov_b32_e32 v47, v0
	v_mov_b32_e32 v56, v0
	v_mov_b32_e32 v57, v0
	v_mov_b32_e32 v58, v0
	v_mov_b32_e32 v59, v0
	v_mov_b32_e32 v60, v0
	v_mov_b32_e32 v61, v0
	v_mov_b32_e32 v62, v0
	v_mov_b32_e32 v63, v0
	v_mov_b32_e32 v64, v0
	v_mov_b32_e32 v65, v0
	v_mov_b32_e32 v66, v0
	v_mov_b32_e32 v67, v0
	v_mov_b32_e32 v68, v0
	v_mov_b32_e32 v69, v0
	v_mov_b32_e32 v70, v0
	v_mov_b32_e32 v71, v0
	v_mov_b32_e32 v80, v0
	v_mov_b32_e32 v81, v0
	v_mov_b32_e32 v82, v0
	v_mov_b32_e32 v83, v0
	v_mov_b32_e32 v84, v0
	v_mov_b32_e32 v85, v0
	v_mov_b32_e32 v86, v0
	v_mov_b32_e32 v87, v0
	v_mov_b32_e32 v96, v0
	v_mov_b32_e32 v97, v0
	v_mov_b32_e32 v98, v0
	v_mov_b32_e32 v99, v0
	v_mov_b32_e32 v100, v0
	v_mov_b32_e32 v101, v0
	v_mov_b32_e32 v102, v0
	v_mov_b32_e32 v103, v0
	v_mov_b32_e32 v112, v0
	v_mov_b32_e32 v113, v0
	v_mov_b32_e32 v114, v0
	v_mov_b32_e32 v115, v0
	v_mov_b32_e32 v116, v0
	v_mov_b32_e32 v117, v0
	v_mov_b32_e32 v118, v0
	v_mov_b32_e32 v119, v0
	v_mov_b32_e32 v72, v0
	v_mov_b32_e32 v73, v0
	v_mov_b32_e32 v74, v0
	v_mov_b32_e32 v75, v0
	v_mov_b32_e32 v76, v0
	v_mov_b32_e32 v77, v0
	v_mov_b32_e32 v78, v0
	v_mov_b32_e32 v79, v0
	v_mov_b32_e32 v88, v0
	v_mov_b32_e32 v89, v0
	v_mov_b32_e32 v90, v0
	v_mov_b32_e32 v91, v0
	v_mov_b32_e32 v92, v0
	v_mov_b32_e32 v93, v0
	v_mov_b32_e32 v94, v0
	v_mov_b32_e32 v95, v0
	v_mov_b32_e32 v104, v0
	v_mov_b32_e32 v105, v0
	v_mov_b32_e32 v106, v0
	v_mov_b32_e32 v107, v0
	v_mov_b32_e32 v108, v0
	v_mov_b32_e32 v109, v0
	v_mov_b32_e32 v110, v0
	v_mov_b32_e32 v111, v0
	v_mov_b32_e32 v120, v0
	v_mov_b32_e32 v121, v0
	v_mov_b32_e32 v122, v0
	v_mov_b32_e32 v123, v0
	v_mov_b32_e32 v124, v0
	v_mov_b32_e32 v125, v0
	v_mov_b32_e32 v126, v0
	v_mov_b32_e32 v127, v0
	.p2align 6
	s_nop 0
	s_nop 0
	s_nop 0
	s_nop 0
	s_nop 0
	s_nop 0
	s_nop 0

.LBB0_549:
	s_ashr_i32 s39, s38, 31
	s_lshl_b64 s[44:45], s[38:39], 19
	s_add_u32 s44, s54, s44
	s_addc_u32 s45, s55, s45
	s_and_b64 s[46:47], s[4:5], exec
	s_cselect_b32 s39, s45, s49
	s_cselect_b32 s78, s44, s48
	s_ashr_i32 s41, s40, 31
	s_lshl_b64 s[46:47], s[40:41], 19
	s_add_u32 s46, s56, s46
	s_addc_u32 s47, s57, s47
	s_and_b64 s[52:53], s[4:5], exec
	s_cselect_b32 s41, s47, s51
	s_cselect_b32 s79, s46, s50
	s_add_u32 s48, s48, 0x40080
	s_addc_u32 s49, s49, 0
	s_add_u32 s80, s50, 0x100
	v_mov_b32_e32 v0, 0
	s_addc_u32 s81, s51, 0
	s_mov_b32 s82, -2
	v_mov_b32_e32 v1, v0
	v_mov_b32_e32 v2, v0
	v_mov_b32_e32 v3, v0
	v_mov_b32_e32 v4, v0
	v_mov_b32_e32 v5, v0
	v_mov_b32_e32 v6, v0
	v_mov_b32_e32 v7, v0
	v_mov_b32_e32 v8, v0
	v_mov_b32_e32 v9, v0
	v_mov_b32_e32 v10, v0
	v_mov_b32_e32 v11, v0
	v_mov_b32_e32 v12, v0
	v_mov_b32_e32 v13, v0
	v_mov_b32_e32 v14, v0
	v_mov_b32_e32 v15, v0
	v_mov_b32_e32 v24, v0
	v_mov_b32_e32 v25, v0
	v_mov_b32_e32 v26, v0
	v_mov_b32_e32 v27, v0
	v_mov_b32_e32 v28, v0
	v_mov_b32_e32 v29, v0
	v_mov_b32_e32 v30, v0
	v_mov_b32_e32 v31, v0
	v_mov_b32_e32 v40, v0
	v_mov_b32_e32 v41, v0
	v_mov_b32_e32 v42, v0
	v_mov_b32_e32 v43, v0
	v_mov_b32_e32 v44, v0
	v_mov_b32_e32 v45, v0
	v_mov_b32_e32 v46, v0
	v_mov_b32_e32 v47, v0
	v_mov_b32_e32 v16, v0
	v_mov_b32_e32 v17, v0
	v_mov_b32_e32 v18, v0
	v_mov_b32_e32 v19, v0
	v_mov_b32_e32 v20, v0
	v_mov_b32_e32 v21, v0
	v_mov_b32_e32 v22, v0
	v_mov_b32_e32 v23, v0
	v_mov_b32_e32 v32, v0
	v_mov_b32_e32 v33, v0
	v_mov_b32_e32 v34, v0
	v_mov_b32_e32 v35, v0
	v_mov_b32_e32 v36, v0
	v_mov_b32_e32 v37, v0
	v_mov_b32_e32 v38, v0
	v_mov_b32_e32 v39, v0
	v_mov_b32_e32 v48, v0
	v_mov_b32_e32 v49, v0
	v_mov_b32_e32 v50, v0
	v_mov_b32_e32 v51, v0
	v_mov_b32_e32 v52, v0
	v_mov_b32_e32 v53, v0
	v_mov_b32_e32 v54, v0
	v_mov_b32_e32 v55, v0
	v_mov_b32_e32 v56, v0
	v_mov_b32_e32 v57, v0
	v_mov_b32_e32 v58, v0
	v_mov_b32_e32 v59, v0
	v_mov_b32_e32 v60, v0
	v_mov_b32_e32 v61, v0
	v_mov_b32_e32 v62, v0
	v_mov_b32_e32 v63, v0
	v_mov_b32_e32 v64, v0
	v_mov_b32_e32 v65, v0
	v_mov_b32_e32 v66, v0
	v_mov_b32_e32 v67, v0
	v_mov_b32_e32 v68, v0
	v_mov_b32_e32 v69, v0
	v_mov_b32_e32 v70, v0
	v_mov_b32_e32 v71, v0
	v_mov_b32_e32 v72, v0
	v_mov_b32_e32 v73, v0
	v_mov_b32_e32 v74, v0
	v_mov_b32_e32 v75, v0
	v_mov_b32_e32 v76, v0
	v_mov_b32_e32 v77, v0
	v_mov_b32_e32 v78, v0
	v_mov_b32_e32 v79, v0
	v_mov_b32_e32 v88, v0
	v_mov_b32_e32 v89, v0
	v_mov_b32_e32 v90, v0
	v_mov_b32_e32 v91, v0
	v_mov_b32_e32 v92, v0
	v_mov_b32_e32 v93, v0
	v_mov_b32_e32 v94, v0
	v_mov_b32_e32 v95, v0
	v_mov_b32_e32 v104, v0
	v_mov_b32_e32 v105, v0
	v_mov_b32_e32 v106, v0
	v_mov_b32_e32 v107, v0
	v_mov_b32_e32 v108, v0
	v_mov_b32_e32 v109, v0
	v_mov_b32_e32 v110, v0
	v_mov_b32_e32 v111, v0
	v_mov_b32_e32 v80, v0
	v_mov_b32_e32 v81, v0
	v_mov_b32_e32 v82, v0
	v_mov_b32_e32 v83, v0
	v_mov_b32_e32 v84, v0
	v_mov_b32_e32 v85, v0
	v_mov_b32_e32 v86, v0
	v_mov_b32_e32 v87, v0
	v_mov_b32_e32 v96, v0
	v_mov_b32_e32 v97, v0
	v_mov_b32_e32 v98, v0
	v_mov_b32_e32 v99, v0
	v_mov_b32_e32 v100, v0
	v_mov_b32_e32 v101, v0
	v_mov_b32_e32 v102, v0
	v_mov_b32_e32 v103, v0
	v_mov_b32_e32 v112, v0
	v_mov_b32_e32 v113, v0
	v_mov_b32_e32 v114, v0
	v_mov_b32_e32 v115, v0
	v_mov_b32_e32 v116, v0
	v_mov_b32_e32 v117, v0
	v_mov_b32_e32 v118, v0
	v_mov_b32_e32 v119, v0
	v_mov_b32_e32 v120, v0
	v_mov_b32_e32 v121, v0
	v_mov_b32_e32 v122, v0
	v_mov_b32_e32 v123, v0
	v_mov_b32_e32 v124, v0
	v_mov_b32_e32 v125, v0
	v_mov_b32_e32 v126, v0
	v_mov_b32_e32 v127, v0
	.p2align 6
	s_nop 0
	s_nop 0
	s_nop 0
	s_nop 0
	s_nop 0
	s_nop 0
	s_nop 0

.LBB0_678:
	s_ashr_i32 s41, s40, 31
	s_lshl_b64 s[42:43], s[40:41], 19
	s_add_u32 s42, s54, s42
	s_addc_u32 s43, s55, s43
	s_and_b64 s[44:45], s[4:5], exec
	s_cselect_b32 s41, s43, s49
	s_cselect_b32 s79, s42, s48
	s_ashr_i32 s39, s38, 31
	s_lshl_b64 s[44:45], s[38:39], 19
	s_add_u32 s44, s56, s44
	s_addc_u32 s45, s57, s45
	s_and_b64 s[52:53], s[4:5], exec
	s_cselect_b32 s39, s45, s51
	s_cselect_b32 s80, s44, s50
	s_add_u32 s48, s48, 0x40080
	s_addc_u32 s49, s49, 0
	s_add_u32 s81, s50, 0x100
	v_mov_b32_e32 v0, 0
	s_addc_u32 s82, s51, 0
	s_mov_b32 s83, -2
	v_mov_b32_e32 v1, v0
	v_mov_b32_e32 v2, v0
	v_mov_b32_e32 v3, v0
	v_mov_b32_e32 v4, v0
	v_mov_b32_e32 v5, v0
	v_mov_b32_e32 v6, v0
	v_mov_b32_e32 v7, v0
	v_mov_b32_e32 v16, v0
	v_mov_b32_e32 v17, v0
	v_mov_b32_e32 v18, v0
	v_mov_b32_e32 v19, v0
	v_mov_b32_e32 v20, v0
	v_mov_b32_e32 v21, v0
	v_mov_b32_e32 v22, v0
	v_mov_b32_e32 v23, v0
	v_mov_b32_e32 v32, v0
	v_mov_b32_e32 v33, v0
	v_mov_b32_e32 v34, v0
	v_mov_b32_e32 v35, v0
	v_mov_b32_e32 v36, v0
	v_mov_b32_e32 v37, v0
	v_mov_b32_e32 v38, v0
	v_mov_b32_e32 v39, v0
	v_mov_b32_e32 v48, v0
	v_mov_b32_e32 v49, v0
	v_mov_b32_e32 v50, v0
	v_mov_b32_e32 v51, v0
	v_mov_b32_e32 v52, v0
	v_mov_b32_e32 v53, v0
	v_mov_b32_e32 v54, v0
	v_mov_b32_e32 v55, v0
	v_mov_b32_e32 v8, v0
	v_mov_b32_e32 v9, v0
	v_mov_b32_e32 v10, v0
	v_mov_b32_e32 v11, v0
	v_mov_b32_e32 v12, v0
	v_mov_b32_e32 v13, v0
	v_mov_b32_e32 v14, v0
	v_mov_b32_e32 v15, v0
	v_mov_b32_e32 v24, v0
	v_mov_b32_e32 v25, v0
	v_mov_b32_e32 v26, v0
	v_mov_b32_e32 v27, v0
	v_mov_b32_e32 v28, v0
	v_mov_b32_e32 v29, v0
	v_mov_b32_e32 v30, v0
	v_mov_b32_e32 v31, v0
	v_mov_b32_e32 v40, v0
	v_mov_b32_e32 v41, v0
	v_mov_b32_e32 v42, v0
	v_mov_b32_e32 v43, v0
	v_mov_b32_e32 v44, v0
	v_mov_b32_e32 v45, v0
	v_mov_b32_e32 v46, v0
	v_mov_b32_e32 v47, v0
	v_mov_b32_e32 v56, v0
	v_mov_b32_e32 v57, v0
	v_mov_b32_e32 v58, v0
	v_mov_b32_e32 v59, v0
	v_mov_b32_e32 v60, v0
	v_mov_b32_e32 v61, v0
	v_mov_b32_e32 v62, v0
	v_mov_b32_e32 v63, v0
	v_mov_b32_e32 v64, v0
	v_mov_b32_e32 v65, v0
	v_mov_b32_e32 v66, v0
	v_mov_b32_e32 v67, v0
	v_mov_b32_e32 v68, v0
	v_mov_b32_e32 v69, v0
	v_mov_b32_e32 v70, v0
	v_mov_b32_e32 v71, v0
	v_mov_b32_e32 v80, v0
	v_mov_b32_e32 v81, v0
	v_mov_b32_e32 v82, v0
	v_mov_b32_e32 v83, v0
	v_mov_b32_e32 v84, v0
	v_mov_b32_e32 v85, v0
	v_mov_b32_e32 v86, v0
	v_mov_b32_e32 v87, v0
	v_mov_b32_e32 v96, v0
	v_mov_b32_e32 v97, v0
	v_mov_b32_e32 v98, v0
	v_mov_b32_e32 v99, v0
	v_mov_b32_e32 v100, v0
	v_mov_b32_e32 v101, v0
	v_mov_b32_e32 v102, v0
	v_mov_b32_e32 v103, v0
	v_mov_b32_e32 v112, v0
	v_mov_b32_e32 v113, v0
	v_mov_b32_e32 v114, v0
	v_mov_b32_e32 v115, v0
	v_mov_b32_e32 v116, v0
	v_mov_b32_e32 v117, v0
	v_mov_b32_e32 v118, v0
	v_mov_b32_e32 v119, v0
	v_mov_b32_e32 v72, v0
	v_mov_b32_e32 v73, v0
	v_mov_b32_e32 v74, v0
	v_mov_b32_e32 v75, v0
	v_mov_b32_e32 v76, v0
	v_mov_b32_e32 v77, v0
	v_mov_b32_e32 v78, v0
	v_mov_b32_e32 v79, v0
	v_mov_b32_e32 v88, v0
	v_mov_b32_e32 v89, v0
	v_mov_b32_e32 v90, v0
	v_mov_b32_e32 v91, v0
	v_mov_b32_e32 v92, v0
	v_mov_b32_e32 v93, v0
	v_mov_b32_e32 v94, v0
	v_mov_b32_e32 v95, v0
	v_mov_b32_e32 v104, v0
	v_mov_b32_e32 v105, v0
	v_mov_b32_e32 v106, v0
	v_mov_b32_e32 v107, v0
	v_mov_b32_e32 v108, v0
	v_mov_b32_e32 v109, v0
	v_mov_b32_e32 v110, v0
	v_mov_b32_e32 v111, v0
	v_mov_b32_e32 v120, v0
	v_mov_b32_e32 v121, v0
	v_mov_b32_e32 v122, v0
	v_mov_b32_e32 v123, v0
	v_mov_b32_e32 v124, v0
	v_mov_b32_e32 v125, v0
	v_mov_b32_e32 v126, v0
	v_mov_b32_e32 v127, v0
	.p2align 6
	s_nop 0
	s_nop 0
	s_nop 0
	s_nop 0
	s_nop 0
	s_nop 0
	s_nop 0

.Lsk8_zero:
	v_mov_b32_e32 v0, 0
	v_mov_b32_e32 v1, v0
	v_mov_b32_e32 v2, v0
	v_mov_b32_e32 v3, v0
	v_mov_b32_e32 v4, v0
	v_mov_b32_e32 v5, v0
	v_mov_b32_e32 v6, v0
	v_mov_b32_e32 v7, v0
	v_mov_b32_e32 v8, v0
	v_mov_b32_e32 v9, v0
	v_mov_b32_e32 v10, v0
	v_mov_b32_e32 v11, v0
	v_mov_b32_e32 v12, v0
	v_mov_b32_e32 v13, v0
	v_mov_b32_e32 v14, v0
	v_mov_b32_e32 v15, v0
	v_mov_b32_e32 v24, v0
	v_mov_b32_e32 v25, v0
	v_mov_b32_e32 v26, v0
	v_mov_b32_e32 v27, v0
	v_mov_b32_e32 v28, v0
	v_mov_b32_e32 v29, v0
	v_mov_b32_e32 v30, v0
	v_mov_b32_e32 v31, v0
	v_mov_b32_e32 v40, v0
	v_mov_b32_e32 v41, v0
	v_mov_b32_e32 v42, v0
	v_mov_b32_e32 v43, v0
	v_mov_b32_e32 v44, v0
	v_mov_b32_e32 v45, v0
	v_mov_b32_e32 v46, v0
	v_mov_b32_e32 v47, v0
	v_mov_b32_e32 v16, v0
	v_mov_b32_e32 v17, v0
	v_mov_b32_e32 v18, v0
	v_mov_b32_e32 v19, v0
	v_mov_b32_e32 v20, v0
	v_mov_b32_e32 v21, v0
	v_mov_b32_e32 v22, v0
	v_mov_b32_e32 v23, v0
	v_mov_b32_e32 v32, v0
	v_mov_b32_e32 v33, v0
	v_mov_b32_e32 v34, v0
	v_mov_b32_e32 v35, v0
	v_mov_b32_e32 v36, v0
	v_mov_b32_e32 v37, v0
	v_mov_b32_e32 v38, v0
	v_mov_b32_e32 v39, v0
	v_mov_b32_e32 v48, v0
	v_mov_b32_e32 v49, v0
	v_mov_b32_e32 v50, v0
	v_mov_b32_e32 v51, v0
	v_mov_b32_e32 v52, v0
	v_mov_b32_e32 v53, v0
	v_mov_b32_e32 v54, v0
	v_mov_b32_e32 v55, v0
	v_mov_b32_e32 v56, v0
	v_mov_b32_e32 v57, v0
	v_mov_b32_e32 v58, v0
	v_mov_b32_e32 v59, v0
	v_mov_b32_e32 v60, v0
	v_mov_b32_e32 v61, v0
	v_mov_b32_e32 v62, v0
	v_mov_b32_e32 v63, v0
	v_mov_b32_e32 v64, v0
	v_mov_b32_e32 v65, v0
	v_mov_b32_e32 v66, v0
	v_mov_b32_e32 v67, v0
	v_mov_b32_e32 v68, v0
	v_mov_b32_e32 v69, v0
	v_mov_b32_e32 v70, v0
	v_mov_b32_e32 v71, v0
	v_mov_b32_e32 v72, v0
	v_mov_b32_e32 v73, v0
	v_mov_b32_e32 v74, v0
	v_mov_b32_e32 v75, v0
	v_mov_b32_e32 v76, v0
	v_mov_b32_e32 v77, v0
	v_mov_b32_e32 v78, v0
	v_mov_b32_e32 v79, v0
	v_mov_b32_e32 v88, v0
	v_mov_b32_e32 v89, v0
	v_mov_b32_e32 v90, v0
	v_mov_b32_e32 v91, v0
	v_mov_b32_e32 v92, v0
	v_mov_b32_e32 v93, v0
	v_mov_b32_e32 v94, v0
	v_mov_b32_e32 v95, v0
	v_mov_b32_e32 v104, v0
	v_mov_b32_e32 v105, v0
	v_mov_b32_e32 v106, v0
	v_mov_b32_e32 v107, v0
	v_mov_b32_e32 v108, v0
	v_mov_b32_e32 v109, v0
	v_mov_b32_e32 v110, v0
	v_mov_b32_e32 v111, v0
	v_mov_b32_e32 v80, v0
	v_mov_b32_e32 v81, v0
	v_mov_b32_e32 v82, v0
	v_mov_b32_e32 v83, v0
	v_mov_b32_e32 v84, v0
	v_mov_b32_e32 v85, v0
	v_mov_b32_e32 v86, v0
	v_mov_b32_e32 v87, v0
	v_mov_b32_e32 v96, v0
	v_mov_b32_e32 v97, v0
	v_mov_b32_e32 v98, v0
	v_mov_b32_e32 v99, v0
	v_mov_b32_e32 v100, v0
	v_mov_b32_e32 v101, v0
	v_mov_b32_e32 v102, v0
	v_mov_b32_e32 v103, v0
	v_mov_b32_e32 v112, v0
	v_mov_b32_e32 v113, v0
	v_mov_b32_e32 v114, v0
	v_mov_b32_e32 v115, v0
	v_mov_b32_e32 v116, v0
	v_mov_b32_e32 v117, v0
	v_mov_b32_e32 v118, v0
	v_mov_b32_e32 v119, v0
	v_mov_b32_e32 v120, v0
	v_mov_b32_e32 v121, v0
	v_mov_b32_e32 v122, v0
	v_mov_b32_e32 v123, v0
	v_mov_b32_e32 v124, v0
	v_mov_b32_e32 v125, v0
	v_mov_b32_e32 v126, v0
	v_mov_b32_e32 v127, v0
	.p2align 6
	s_nop 0
	s_nop 0
	s_nop 0
	s_nop 0
	s_nop 0
	s_nop 0
	s_nop 0

.LBB0_880:
	s_ashr_i32 s43, s42, 31
	s_lshl_b64 s[44:45], s[42:43], 19
	s_add_u32 s44, s54, s44
	s_addc_u32 s45, s55, s45
	s_and_b64 s[46:47], s[4:5], exec
	s_cselect_b32 s7, s45, s49
	s_cselect_b32 s9, s44, s48
	s_ashr_i32 s41, s40, 31
	s_lshl_b64 s[46:47], s[40:41], 19
	s_add_u32 s46, s56, s46
	s_addc_u32 s47, s57, s47
	s_and_b64 s[52:53], s[4:5], exec
	s_cselect_b32 s41, s47, s51
	s_cselect_b32 s43, s46, s50
	s_add_u32 s48, s48, 0x40080
	s_addc_u32 s49, s49, 0
	s_add_u32 s63, s50, 0x100
	v_mov_b32_e32 v0, 0
	s_addc_u32 s77, s51, 0
	s_mov_b32 s78, -2
	v_mov_b32_e32 v1, v0
	v_mov_b32_e32 v2, v0
	v_mov_b32_e32 v3, v0
	v_mov_b32_e32 v4, v0
	v_mov_b32_e32 v5, v0
	v_mov_b32_e32 v6, v0
	v_mov_b32_e32 v7, v0
	v_mov_b32_e32 v16, v0
	v_mov_b32_e32 v17, v0
	v_mov_b32_e32 v18, v0
	v_mov_b32_e32 v19, v0
	v_mov_b32_e32 v20, v0
	v_mov_b32_e32 v21, v0
	v_mov_b32_e32 v22, v0
	v_mov_b32_e32 v23, v0
	v_mov_b32_e32 v32, v0
	v_mov_b32_e32 v33, v0
	v_mov_b32_e32 v34, v0
	v_mov_b32_e32 v35, v0
	v_mov_b32_e32 v36, v0
	v_mov_b32_e32 v37, v0
	v_mov_b32_e32 v38, v0
	v_mov_b32_e32 v39, v0
	v_mov_b32_e32 v48, v0
	v_mov_b32_e32 v49, v0
	v_mov_b32_e32 v50, v0
	v_mov_b32_e32 v51, v0
	v_mov_b32_e32 v52, v0
	v_mov_b32_e32 v53, v0
	v_mov_b32_e32 v54, v0
	v_mov_b32_e32 v55, v0
	v_mov_b32_e32 v8, v0
	v_mov_b32_e32 v9, v0
	v_mov_b32_e32 v10, v0
	v_mov_b32_e32 v11, v0
	v_mov_b32_e32 v12, v0
	v_mov_b32_e32 v13, v0
	v_mov_b32_e32 v14, v0
	v_mov_b32_e32 v15, v0
	v_mov_b32_e32 v24, v0
	v_mov_b32_e32 v25, v0
	v_mov_b32_e32 v26, v0
	v_mov_b32_e32 v27, v0
	v_mov_b32_e32 v28, v0
	v_mov_b32_e32 v29, v0
	v_mov_b32_e32 v30, v0
	v_mov_b32_e32 v31, v0
	v_mov_b32_e32 v40, v0
	v_mov_b32_e32 v41, v0
	v_mov_b32_e32 v42, v0
	v_mov_b32_e32 v43, v0
	v_mov_b32_e32 v44, v0
	v_mov_b32_e32 v45, v0
	v_mov_b32_e32 v46, v0
	v_mov_b32_e32 v47, v0
	v_mov_b32_e32 v56, v0
	v_mov_b32_e32 v57, v0
	v_mov_b32_e32 v58, v0
	v_mov_b32_e32 v59, v0
	v_mov_b32_e32 v60, v0
	v_mov_b32_e32 v61, v0
	v_mov_b32_e32 v62, v0
	v_mov_b32_e32 v63, v0
	v_mov_b32_e32 v64, v0
	v_mov_b32_e32 v65, v0
	v_mov_b32_e32 v66, v0
	v_mov_b32_e32 v67, v0
	v_mov_b32_e32 v68, v0
	v_mov_b32_e32 v69, v0
	v_mov_b32_e32 v70, v0
	v_mov_b32_e32 v71, v0
	v_mov_b32_e32 v80, v0
	v_mov_b32_e32 v81, v0
	v_mov_b32_e32 v82, v0
	v_mov_b32_e32 v83, v0
	v_mov_b32_e32 v84, v0
	v_mov_b32_e32 v85, v0
	v_mov_b32_e32 v86, v0
	v_mov_b32_e32 v87, v0
	v_mov_b32_e32 v96, v0
	v_mov_b32_e32 v97, v0
	v_mov_b32_e32 v98, v0
	v_mov_b32_e32 v99, v0
	v_mov_b32_e32 v100, v0
	v_mov_b32_e32 v101, v0
	v_mov_b32_e32 v102, v0
	v_mov_b32_e32 v103, v0
	v_mov_b32_e32 v112, v0
	v_mov_b32_e32 v113, v0
	v_mov_b32_e32 v114, v0
	v_mov_b32_e32 v115, v0
	v_mov_b32_e32 v116, v0
	v_mov_b32_e32 v117, v0
	v_mov_b32_e32 v118, v0
	v_mov_b32_e32 v119, v0
	v_mov_b32_e32 v72, v0
	v_mov_b32_e32 v73, v0
	v_mov_b32_e32 v74, v0
	v_mov_b32_e32 v75, v0
	v_mov_b32_e32 v76, v0
	v_mov_b32_e32 v77, v0
	v_mov_b32_e32 v78, v0
	v_mov_b32_e32 v79, v0
	v_mov_b32_e32 v88, v0
	v_mov_b32_e32 v89, v0
	v_mov_b32_e32 v90, v0
	v_mov_b32_e32 v91, v0
	v_mov_b32_e32 v92, v0
	v_mov_b32_e32 v93, v0
	v_mov_b32_e32 v94, v0
	v_mov_b32_e32 v95, v0
	v_mov_b32_e32 v104, v0
	v_mov_b32_e32 v105, v0
	v_mov_b32_e32 v106, v0
	v_mov_b32_e32 v107, v0
	v_mov_b32_e32 v108, v0
	v_mov_b32_e32 v109, v0
	v_mov_b32_e32 v110, v0
	v_mov_b32_e32 v111, v0
	v_mov_b32_e32 v120, v0
	v_mov_b32_e32 v121, v0
	v_mov_b32_e32 v122, v0
	v_mov_b32_e32 v123, v0
	v_mov_b32_e32 v124, v0
	v_mov_b32_e32 v125, v0
	v_mov_b32_e32 v126, v0
	v_mov_b32_e32 v127, v0
	.p2align 6
	s_nop 0
	s_nop 0
	s_nop 0
	s_nop 0
	s_nop 0
	s_nop 0
	s_nop 0

.LBB0_1143:
	s_ashr_i32 s31, s30, 31
	s_lshl_b64 s[38:39], s[30:31], 19
	s_add_u32 s38, s48, s38
	s_addc_u32 s39, s49, s39
	s_and_b64 s[40:41], s[4:5], exec
	s_cselect_b32 s31, s39, s43
	s_cselect_b32 s71, s38, s42
	s_ashr_i32 s35, s34, 31
	s_lshl_b64 s[40:41], s[34:35], 19
	s_add_u32 s40, s50, s40
	s_addc_u32 s41, s51, s41
	s_and_b64 s[46:47], s[4:5], exec
	s_cselect_b32 s35, s41, s45
	s_cselect_b32 s72, s40, s44
	s_add_u32 s42, s42, 0x40080
	s_addc_u32 s43, s43, 0
	s_add_u32 s73, s44, 0x100
	v_mov_b32_e32 v0, 0
	s_addc_u32 s74, s45, 0
	s_mov_b32 s75, -2
	v_mov_b32_e32 v1, v0
	v_mov_b32_e32 v2, v0
	v_mov_b32_e32 v3, v0
	v_mov_b32_e32 v4, v0
	v_mov_b32_e32 v5, v0
	v_mov_b32_e32 v6, v0
	v_mov_b32_e32 v7, v0
	v_mov_b32_e32 v8, v0
	v_mov_b32_e32 v9, v0
	v_mov_b32_e32 v10, v0
	v_mov_b32_e32 v11, v0
	v_mov_b32_e32 v12, v0
	v_mov_b32_e32 v13, v0
	v_mov_b32_e32 v14, v0
	v_mov_b32_e32 v15, v0
	v_mov_b32_e32 v24, v0
	v_mov_b32_e32 v25, v0
	v_mov_b32_e32 v26, v0
	v_mov_b32_e32 v27, v0
	v_mov_b32_e32 v28, v0
	v_mov_b32_e32 v29, v0
	v_mov_b32_e32 v30, v0
	v_mov_b32_e32 v31, v0
	v_mov_b32_e32 v40, v0
	v_mov_b32_e32 v41, v0
	v_mov_b32_e32 v42, v0
	v_mov_b32_e32 v43, v0
	v_mov_b32_e32 v44, v0
	v_mov_b32_e32 v45, v0
	v_mov_b32_e32 v46, v0
	v_mov_b32_e32 v47, v0
	v_mov_b32_e32 v16, v0
	v_mov_b32_e32 v17, v0
	v_mov_b32_e32 v18, v0
	v_mov_b32_e32 v19, v0
	v_mov_b32_e32 v20, v0
	v_mov_b32_e32 v21, v0
	v_mov_b32_e32 v22, v0
	v_mov_b32_e32 v23, v0
	v_mov_b32_e32 v32, v0
	v_mov_b32_e32 v33, v0
	v_mov_b32_e32 v34, v0
	v_mov_b32_e32 v35, v0
	v_mov_b32_e32 v36, v0
	v_mov_b32_e32 v37, v0
	v_mov_b32_e32 v38, v0
	v_mov_b32_e32 v39, v0
	v_mov_b32_e32 v48, v0
	v_mov_b32_e32 v49, v0
	v_mov_b32_e32 v50, v0
	v_mov_b32_e32 v51, v0
	v_mov_b32_e32 v52, v0
	v_mov_b32_e32 v53, v0
	v_mov_b32_e32 v54, v0
	v_mov_b32_e32 v55, v0
	v_mov_b32_e32 v56, v0
	v_mov_b32_e32 v57, v0
	v_mov_b32_e32 v58, v0
	v_mov_b32_e32 v59, v0
	v_mov_b32_e32 v60, v0
	v_mov_b32_e32 v61, v0
	v_mov_b32_e32 v62, v0
	v_mov_b32_e32 v63, v0
	v_mov_b32_e32 v64, v0
	v_mov_b32_e32 v65, v0
	v_mov_b32_e32 v66, v0
	v_mov_b32_e32 v67, v0
	v_mov_b32_e32 v68, v0
	v_mov_b32_e32 v69, v0
	v_mov_b32_e32 v70, v0
	v_mov_b32_e32 v71, v0
	v_mov_b32_e32 v72, v0
	v_mov_b32_e32 v73, v0
	v_mov_b32_e32 v74, v0
	v_mov_b32_e32 v75, v0
	v_mov_b32_e32 v76, v0
	v_mov_b32_e32 v77, v0
	v_mov_b32_e32 v78, v0
	v_mov_b32_e32 v79, v0
	v_mov_b32_e32 v88, v0
	v_mov_b32_e32 v89, v0
	v_mov_b32_e32 v90, v0
	v_mov_b32_e32 v91, v0
	v_mov_b32_e32 v92, v0
	v_mov_b32_e32 v93, v0
	v_mov_b32_e32 v94, v0
	v_mov_b32_e32 v95, v0
	v_mov_b32_e32 v104, v0
	v_mov_b32_e32 v105, v0
	v_mov_b32_e32 v106, v0
	v_mov_b32_e32 v107, v0
	v_mov_b32_e32 v108, v0
	v_mov_b32_e32 v109, v0
	v_mov_b32_e32 v110, v0
	v_mov_b32_e32 v111, v0
	v_mov_b32_e32 v80, v0
	v_mov_b32_e32 v81, v0
	v_mov_b32_e32 v82, v0
	v_mov_b32_e32 v83, v0
	v_mov_b32_e32 v84, v0
	v_mov_b32_e32 v85, v0
	v_mov_b32_e32 v86, v0
	v_mov_b32_e32 v87, v0
	v_mov_b32_e32 v96, v0
	v_mov_b32_e32 v97, v0
	v_mov_b32_e32 v98, v0
	v_mov_b32_e32 v99, v0
	v_mov_b32_e32 v100, v0
	v_mov_b32_e32 v101, v0
	v_mov_b32_e32 v102, v0
	v_mov_b32_e32 v103, v0
	v_mov_b32_e32 v112, v0
	v_mov_b32_e32 v113, v0
	v_mov_b32_e32 v114, v0
	v_mov_b32_e32 v115, v0
	v_mov_b32_e32 v116, v0
	v_mov_b32_e32 v117, v0
	v_mov_b32_e32 v118, v0
	v_mov_b32_e32 v119, v0
	v_mov_b32_e32 v120, v0
	v_mov_b32_e32 v121, v0
	v_mov_b32_e32 v122, v0
	v_mov_b32_e32 v123, v0
	v_mov_b32_e32 v124, v0
	v_mov_b32_e32 v125, v0
	v_mov_b32_e32 v126, v0
	v_mov_b32_e32 v127, v0
	.p2align 6
	s_nop 0
	s_nop 0
	s_nop 0
	s_nop 0
	s_nop 0
	s_nop 0
	s_nop 0

.LBB0_1302:
	s_ashr_i32 s31, s30, 31
	s_lshl_b64 s[34:35], s[30:31], 19
	s_add_u32 s34, s47, s34
	s_addc_u32 s35, s48, s35
	s_and_b64 s[36:37], s[4:5], exec
	s_cselect_b32 s31, s35, s41
	s_cselect_b32 s71, s34, s40
	s_ashr_i32 s29, s28, 31
	s_lshl_b64 s[36:37], s[28:29], 19
	s_add_u32 s36, s49, s36
	s_addc_u32 s37, s50, s37
	s_and_b64 s[44:45], s[4:5], exec
	s_cselect_b32 s29, s37, s43
	s_cselect_b32 s72, s36, s42
	s_add_u32 s40, s40, 0x40080
	s_addc_u32 s41, s41, 0
	s_add_u32 s73, s42, 0x100
	v_mov_b32_e32 v0, 0
	s_addc_u32 s74, s43, 0
	s_mov_b32 s75, -2
	v_mov_b32_e32 v1, v0
	v_mov_b32_e32 v2, v0
	v_mov_b32_e32 v3, v0
	v_mov_b32_e32 v4, v0
	v_mov_b32_e32 v5, v0
	v_mov_b32_e32 v6, v0
	v_mov_b32_e32 v7, v0
	v_mov_b32_e32 v16, v0
	v_mov_b32_e32 v17, v0
	v_mov_b32_e32 v18, v0
	v_mov_b32_e32 v19, v0
	v_mov_b32_e32 v20, v0
	v_mov_b32_e32 v21, v0
	v_mov_b32_e32 v22, v0
	v_mov_b32_e32 v23, v0
	v_mov_b32_e32 v32, v0
	v_mov_b32_e32 v33, v0
	v_mov_b32_e32 v34, v0
	v_mov_b32_e32 v35, v0
	v_mov_b32_e32 v36, v0
	v_mov_b32_e32 v37, v0
	v_mov_b32_e32 v38, v0
	v_mov_b32_e32 v39, v0
	v_mov_b32_e32 v48, v0
	v_mov_b32_e32 v49, v0
	v_mov_b32_e32 v50, v0
	v_mov_b32_e32 v51, v0
	v_mov_b32_e32 v52, v0
	v_mov_b32_e32 v53, v0
	v_mov_b32_e32 v54, v0
	v_mov_b32_e32 v55, v0
	v_mov_b32_e32 v8, v0
	v_mov_b32_e32 v9, v0
	v_mov_b32_e32 v10, v0
	v_mov_b32_e32 v11, v0
	v_mov_b32_e32 v12, v0
	v_mov_b32_e32 v13, v0
	v_mov_b32_e32 v14, v0
	v_mov_b32_e32 v15, v0
	v_mov_b32_e32 v24, v0
	v_mov_b32_e32 v25, v0
	v_mov_b32_e32 v26, v0
	v_mov_b32_e32 v27, v0
	v_mov_b32_e32 v28, v0
	v_mov_b32_e32 v29, v0
	v_mov_b32_e32 v30, v0
	v_mov_b32_e32 v31, v0
	v_mov_b32_e32 v40, v0
	v_mov_b32_e32 v41, v0
	v_mov_b32_e32 v42, v0
	v_mov_b32_e32 v43, v0
	v_mov_b32_e32 v44, v0
	v_mov_b32_e32 v45, v0
	v_mov_b32_e32 v46, v0
	v_mov_b32_e32 v47, v0
	v_mov_b32_e32 v56, v0
	v_mov_b32_e32 v57, v0
	v_mov_b32_e32 v58, v0
	v_mov_b32_e32 v59, v0
	v_mov_b32_e32 v60, v0
	v_mov_b32_e32 v61, v0
	v_mov_b32_e32 v62, v0
	v_mov_b32_e32 v63, v0
	v_mov_b32_e32 v64, v0
	v_mov_b32_e32 v65, v0
	v_mov_b32_e32 v66, v0
	v_mov_b32_e32 v67, v0
	v_mov_b32_e32 v68, v0
	v_mov_b32_e32 v69, v0
	v_mov_b32_e32 v70, v0
	v_mov_b32_e32 v71, v0
	v_mov_b32_e32 v80, v0
	v_mov_b32_e32 v81, v0
	v_mov_b32_e32 v82, v0
	v_mov_b32_e32 v83, v0
	v_mov_b32_e32 v84, v0
	v_mov_b32_e32 v85, v0
	v_mov_b32_e32 v86, v0
	v_mov_b32_e32 v87, v0
	v_mov_b32_e32 v96, v0
	v_mov_b32_e32 v97, v0
	v_mov_b32_e32 v98, v0
	v_mov_b32_e32 v99, v0
	v_mov_b32_e32 v100, v0
	v_mov_b32_e32 v101, v0
	v_mov_b32_e32 v102, v0
	v_mov_b32_e32 v103, v0
	v_mov_b32_e32 v112, v0
	v_mov_b32_e32 v113, v0
	v_mov_b32_e32 v114, v0
	v_mov_b32_e32 v115, v0
	v_mov_b32_e32 v116, v0
	v_mov_b32_e32 v117, v0
	v_mov_b32_e32 v118, v0
	v_mov_b32_e32 v119, v0
	v_mov_b32_e32 v72, v0
	v_mov_b32_e32 v73, v0
	v_mov_b32_e32 v74, v0
	v_mov_b32_e32 v75, v0
	v_mov_b32_e32 v76, v0
	v_mov_b32_e32 v77, v0
	v_mov_b32_e32 v78, v0
	v_mov_b32_e32 v79, v0
	v_mov_b32_e32 v88, v0
	v_mov_b32_e32 v89, v0
	v_mov_b32_e32 v90, v0
	v_mov_b32_e32 v91, v0
	v_mov_b32_e32 v92, v0
	v_mov_b32_e32 v93, v0
	v_mov_b32_e32 v94, v0
	v_mov_b32_e32 v95, v0
	v_mov_b32_e32 v104, v0
	v_mov_b32_e32 v105, v0
	v_mov_b32_e32 v106, v0
	v_mov_b32_e32 v107, v0
	v_mov_b32_e32 v108, v0
	v_mov_b32_e32 v109, v0
	v_mov_b32_e32 v110, v0
	v_mov_b32_e32 v111, v0
	v_mov_b32_e32 v120, v0
	v_mov_b32_e32 v121, v0
	v_mov_b32_e32 v122, v0
	v_mov_b32_e32 v123, v0
	v_mov_b32_e32 v124, v0
	v_mov_b32_e32 v125, v0
	v_mov_b32_e32 v126, v0
	v_mov_b32_e32 v127, v0
	.p2align 6
	s_nop 0
	s_nop 0
	s_nop 0
	s_nop 0
	s_nop 0
	s_nop 0
	s_nop 0
